# scan: k*v rows computed by the four main producer waves, waves 4/5 only reduce+store y (SIMD load rebalancing), v30 consumer, nt row loads
# baseline (speedup 1.0000x reference)
; #define LAS __attribute__((address_space(3)))
; DI unsigned pk2(float lo, float hi) { f32x2 v = {lo, hi}; bf16x2_t b = __builtin_convertvector(v, bf16x2_t); return __builtin_bit_cast(unsigned, b); }
; DI float row16_sum(float v) { v += dpp_f<0xB1>(v); v += dpp_f<0x4E>(v); v += dpp_f<0x141>(v); v += dpp_f<0x140>(v); return v; }
; DI void rwkv_scan_phase(int wv, const Params& P, LAS unsigned char* lds) {
;     ...
;             const int ch = h * 64 + lane;
;             const float kkw = P.in[35][ch], kaw = P.in[36][ch], rkw = P.in[37][ch];
;             const int hf = lane >> 5, c2 = lane & 31, chp = h * 64 + 2 * c2;
;             const f32x2 kkw2 = *(const f32x2*)(P.in[35] + chp), kaw2 = *(const f32x2*)(P.in[36] + chp), rkw2 = *(const f32x2*)(P.in[37] + chp);
;             unsigned gk[3], ga[3], gr[3], gl[3]; float gv[3];
;     ...
;             RW_LOADG(0)
; #pragma unroll 1
;             for (int ck = -1; ck <= nck; ++ck) {
;                 {
;                     if (ck >= 1) { const LAS float* yb = ybuf + ((ck - 1) & 1) * RW_T * 128;
; #pragma unroll 2
;                         for (int it = pw; it < 64; it += 6) { const float y = row16_sum(yb[it * 64 + lane]);
;                             const float y0 = __builtin_bit_cast(float, __builtin_amdgcn_readlane(__builtin_bit_cast(int, y), 0)), y1 = __builtin_bit_cast(float, __builtin_amdgcn_readlane(__builtin_bit_cast(int, y), 16)),
;                                         y2 = __builtin_bit_cast(float, __builtin_amdgcn_readlane(__builtin_bit_cast(int, y), 32)), y3 = __builtin_bit_cast(float, __builtin_amdgcn_readlane(__builtin_bit_cast(int, y), 48));
;                             if (lane == 0) { u32x2 w; w.x = pk2(y0, y1); w.y = pk2(y2, y3); *(u32x2*)(YS + ((size_t)b * SEQ + (ck - 1) * RW_T + (it >> 1)) * 1024 + h * 64 + rg * 8 + (it & 1) * 4) = w; } } }
;                     if (ck + 1 < nck) { const int cn = ck + 1, buf = cn & 1;
; #pragma unroll
;                         for (int i = 0; i < 3; ++i) { const int pp = pw + 6 * i; if (pp < 16) { const int tt = 2 * pp + hf; const size_t row = (size_t)b * SEQ + cn * RW_T + tt;
.LBB0_3185:
	s_andn2_saveexec_b64 s[40:41], s[20:21]
	s_cbranch_execz .LBB0_3174
	v_readfirstlane_b32 s55, v41
	s_and_b32 s66, s55, 2
	s_cmp_lg_u32 s66, 0
	s_cbranch_scc1 .Lprod_flusher
	s_lshr_b32 s66, s55, 1
	s_and_b32 s55, s55, 1
	s_or_b32 s55, s55, s66
	s_and_b32 s67, s46, 7
	s_bfe_u32 s59, s46, 0x40003
	s_lshr_b32 s60, s46, 7
	s_lshl_b32 s60, s60, 13
	s_lshl_b32 s66, s55, 2
	s_add_i32 s60, s60, s66
	v_mbcnt_lo_u32_b32 v0, -1, 0
	v_mbcnt_hi_u32_b32 v0, -1, v0
	v_and_b32_e32 v1, 31, v0
	v_lshrrev_b32_e32 v31, 5, v0
	s_lshl_b32 s61, s59, 6
	v_lshl_add_u32 v32, v1, 1, s61
	v_lshlrev_b32_e32 v33, 2, v32
	global_load_dwordx2 v[4:5], v33, s[24:25]
	global_load_dwordx2 v[6:7], v33, s[26:27]
	global_load_dwordx2 v[8:9], v33, s[38:39]
	v_add_u32_e32 v34, s60, v31
	v_lshlrev_b32_e32 v35, 11, v34
	v_lshl_add_u32 v12, v32, 1, v35
	v_add_u32_e32 v13, 0x1000, v12
	s_lshl_b32 s66, s67, 3
	s_add_i32 s66, s66, s61
	v_mov_b32_e32 v37, s66
	v_lshl_add_u32 v16, v37, 1, v35
	v_add_u32_e32 v17, 0x1000, v16
	s_lshl_b32 s66, s55, 2
	v_add_u32_e32 v37, s66, v31
	v_mul_u32_u24_e32 v2, 0xc00, v37
	v_lshl_add_u32 v2, v1, 3, v2
	v_and_b32_e32 v80, 1, v1
	v_lshlrev_b32_e32 v80, 8, v80
	v_lshrrev_b32_e32 v81, 1, v1
	v_lshl_add_u32 v80, v81, 4, v80
	v_lshlrev_b32_e32 v81, 3, v1
	v_sub_u32_e32 v80, v80, v81
	s_lshl_b32 s66, s59, 2
	v_lshl_add_u32 v10, v34, 6, s66
	v_or_b32_e32 v38, s67, v1
	v_cmp_eq_u32_e64 s[42:43], 0, v38
	s_mov_b32 s57, -1
	s_mov_b32 s67, 0
	s_waitcnt vmcnt(0)
	s_add_u32 s60, s28, s67
	s_addc_u32 s61, s29, 0
	global_load_dword v44, v12, s[60:61]
	global_load_dword v48, v13, s[60:61]
	s_add_u32 s60, s34, s67
	s_addc_u32 s61, s35, 0
	global_load_dword v45, v12, s[60:61]
	global_load_dword v49, v13, s[60:61]
	s_add_u32 s60, s22, s67
	s_addc_u32 s61, s23, 0
	global_load_dword v46, v12, s[60:61]
	global_load_dword v50, v13, s[60:61]
	s_add_u32 s60, s36, s67
	s_addc_u32 s61, s37, 0
	global_load_dword v47, v12, s[60:61]
	global_load_dword v51, v13, s[60:61]
	s_add_u32 s60, s30, s67
	s_addc_u32 s61, s31, 0
	global_load_dwordx4 v[52:55], v16, s[60:61]
	global_load_dwordx4 v[56:59], v17, s[60:61]
	s_add_u32 s60, s22, s67
	s_addc_u32 s61, s23, 0
	s_sub_u32 s60, s60, 0x800
	s_subb_u32 s61, s61, 0
	global_load_dword v0, v12, s[60:61]
	global_load_dword v40, v13, s[60:61]
	s_mov_b32 s67, 0x8000
	s_add_u32 s60, s28, s67
	s_addc_u32 s61, s29, 0
	global_load_dword v24, v12, s[60:61]
	global_load_dword v28, v13, s[60:61]
	s_add_u32 s60, s34, s67
	s_addc_u32 s61, s35, 0
	global_load_dword v25, v12, s[60:61]
	global_load_dword v29, v13, s[60:61]
	s_add_u32 s60, s22, s67
	s_addc_u32 s61, s23, 0
	global_load_dword v26, v12, s[60:61]
	global_load_dword v30, v13, s[60:61]
	s_add_u32 s60, s36, s67
	s_addc_u32 s61, s37, 0
	global_load_dword v27, v12, s[60:61]
	global_load_dword v31, v13, s[60:61]
	s_add_u32 s60, s30, s67
	s_addc_u32 s61, s31, 0
	global_load_dwordx4 v[32:35], v16, s[60:61]
	global_load_dwordx4 v[36:39], v17, s[60:61]
	s_add_u32 s60, s22, s67
	s_addc_u32 s61, s23, 0
	s_sub_u32 s60, s60, 0x800
	s_subb_u32 s61, s61, 0
	global_load_dword v3, v12, s[60:61]
	global_load_dword v43, v13, s[60:61]
.Lprod_loop:
.Lprod_half_0:
	s_cmp_gt_i32 s57, 0x1fe
	s_cbranch_scc1 .Lprod_sync_0
	s_add_i32 s67, s57, 1
	v_mov_b32_e32 v22, v2
	v_add_u32_e32 v21, v80, v22
	v_mov_b32_e32 v23, 0x1e000
	v_lshl_add_u32 v23, v1, 3, v23
	s_lshl_b32 s60, s67, 10
	s_add_u32 s62, s50, s60
	s_addc_u32 s63, s51, 0
	s_cmp_gt_i32 s57, 0x1fd
	s_cbranch_scc1 .Lprod_w0_0
	s_waitcnt vmcnt(12)
	s_branch .Lprod_wd_0

; #define LAS __attribute__((address_space(3)))
; DI float bflo(unsigned u) { return __uint_as_float(u << 16); }
; DI float bfhi(unsigned u) { return __uint_as_float(u & 0xffff0000u); }
; template <int CTRL> DI float dpp_f(float v) { return __builtin_bit_cast(float, __builtin_amdgcn_update_dpp(0, __builtin_bit_cast(int, v), CTRL, 0xf, 0xf, true)); }
; DI void rwkv_scan_phase(int wv, const Params& P, LAS unsigned char* lds) {
;     ...
;                         for (int i = 0; i < 3; ++i) { const int pp = pw + 6 * i; if (pp < 16) { const int tt = 2 * pp + hf; const size_t row = (size_t)b * SEQ + cn * RW_T + tt;
;                             const f32x2 k = {bflo(gk[i]), bfhi(gk[i])}, a = {bflo(ga[i]), bfhi(ga[i])}, r = {bflo(gr[i]), bfhi(gr[i])};
;                             const h16x2 lh = __builtin_bit_cast(h16x2, gl[i]);
;                             const f32x2 kr = k * kkw2, kp = k * ((a - 1.f) * kaw2 + 1.f);
;                             const float sp = kr[0] * kr[0] + kr[1] * kr[1], rp = r[0] * kp[0] * rkw2[0] + r[1] * kp[1] * rkw2[1];
;                             const bool odd = lane & 1;
;                             float red = (odd ? rp : sp) + dpp_f<0xB1>(odd ? sp : rp);
;                             red += dpp_f<0x4E>(red); red += dpp_f<0x124>(red); red += dpp_f<0x128>(red);
;                             { auto x = __builtin_amdgcn_permlane16_swap(__float_as_uint(red), __float_as_uint(red), false, false); red = __uint_as_float(x[0]) + __uint_as_float(x[1]); }
;                             const float oth = dpp_f<0xB1>(red); const float ss = odd ? oth : red, rks = odd ? red : oth;
;                             const f32x2 kk = kr * __builtin_amdgcn_rsqf(fmaxf(ss, 1e-24f));
;                             LAS float* d = stg + ((buf * RW_T + tt) * 5) * 64 + 2 * c2;
;                             *(LAS f32x2*)(d) = -kk; *(LAS f32x2*)(d + 64) = (f32x2){__expf((float)lh[0]), __expf((float)lh[1])}; *(LAS f32x2*)(d + 128) = kk * a; *(LAS f32x2*)(d + 192) = kp; *(LAS f32x2*)(d + 256) = r;
;                             if (rg == 0 && c2 == 0) RK[row * 16 + h] = rks;
;                             if (c2 < 8) vst[(buf * RW_T + tt) * 8 + c2] = gv[i]; } }
.Lprod_wd_0:
	v_lshlrev_b32_e32 v64, 16, v45
	v_and_b32_e32 v65, 0xffff0000, v45
	v_pk_add_f32 v[72:73], v[64:65], -1.0 op_sel_hi:[1,0]
	v_lshlrev_b32_e32 v66, 16, v44
	v_and_b32_e32 v67, 0xffff0000, v44
	v_pk_fma_f32 v[72:73], v[6:7], v[72:73], 1.0 op_sel_hi:[1,1,0]
	v_and_b32_e32 v69, 0xffff0000, v46
	v_pk_mul_f32 v[70:71], v[4:5], v[66:67]
	v_pk_mul_f32 v[66:67], v[72:73], v[66:67]
	v_lshlrev_b32_e32 v68, 16, v46
	v_mul_f32_e32 v75, v67, v69
	v_pk_mul_f32 v[72:73], v[70:71], v[70:71]
	v_mul_f32_e32 v74, v66, v68
	v_mul_f32_e32 v75, v9, v75
	v_add_f32_e32 v76, v72, v73
	v_fmac_f32_e32 v75, v8, v74
	v_cndmask_b32_e64 v74, v75, v76, s[8:9]
	v_cndmask_b32_e64 v76, v76, v75, s[8:9]
	v_cvt_f32_f16_e32 v77, v47
	v_cvt_f32_f16_sdwa v78, v47 dst_sel:DWORD dst_unused:UNUSED_PAD src0_sel:WORD_1
	v_add_f32_dpp v76, v76, v74 quad_perm:[1,0,3,2] row_mask:0xf bank_mask:0xf bound_ctrl:1
	v_mul_f32_e32 v77, 0x3fb8aa3b, v77
	s_nop 0
	v_add_f32_dpp v76, v76, v76 quad_perm:[2,3,0,1] row_mask:0xf bank_mask:0xf bound_ctrl:1
	v_exp_f32_e32 v72, v77
	v_mul_f32_e32 v77, 0x3fb8aa3b, v78
	v_add_f32_dpp v76, v76, v76 row_ror:4 row_mask:0xf bank_mask:0xf bound_ctrl:1
	v_exp_f32_e32 v73, v77
	s_nop 0
	v_add_f32_dpp v76, v76, v76 row_ror:8 row_mask:0xf bank_mask:0xf bound_ctrl:1
	v_mov_b32_e32 v74, v76
	s_nop 1
	v_permlane16_swap_b32_e32 v76, v74
	v_add_f32_e32 v76, v76, v74
	s_nop 1
	v_mov_b32_dpp v74, v76 quad_perm:[1,0,3,2] row_mask:0xf bank_mask:0xf bound_ctrl:1
	v_cndmask_b32_e64 v75, v74, v76, s[8:9]
	v_max_f32_e32 v75, v75, v75
	v_max_f32_e32 v75, 0x179abe15, v75
	v_rsq_f32_e32 v42, v75
	v_cndmask_b32_e64 v76, v76, v74, s[8:9]
	v_lshlrev_b32_e32 v74, 16, v52
	v_pk_mul_f32 v[70:71], v[70:71], v[42:43] op_sel_hi:[1,0] neg_lo:[0,1] neg_hi:[0,1]
	ds_write_b64 v22, v[72:73] offset:512
	v_and_b32_e32 v75, 0xffff0000, v52
	v_pk_mul_f32 v[64:65], v[70:71], v[64:65] neg_lo:[1,0] neg_hi:[1,0]
	v_mov_b32_e32 v72, v71
	v_lshlrev_b32_e32 v71, 16, v0
	ds_write_b64 v22, v[64:65] offset:768
	v_and_b32_e32 v73, 0xffff0000, v0
	v_pk_mul_f32 v[78:79], v[66:67], v[74:75] op_sel_hi:[1,0]
	ds_write_b128 v21, v[70:73]
	v_pk_mul_f32 v[74:75], v[66:67], v[74:75] op_sel:[0,1] op_sel_hi:[1,1]
	v_lshlrev_b32_e32 v64, 16, v53
	v_and_b32_e32 v65, 0xffff0000, v53
	ds_write_b64 v22, v[78:79] offset:1024
	ds_write_b64 v22, v[74:75] offset:1280
	v_pk_mul_f32 v[70:71], v[66:67], v[64:65] op_sel_hi:[1,0]
	v_pk_mul_f32 v[72:73], v[66:67], v[64:65] op_sel:[0,1] op_sel_hi:[1,1]
	v_lshlrev_b32_e32 v78, 16, v54
	v_and_b32_e32 v79, 0xffff0000, v54
	ds_write_b64 v22, v[70:71] offset:1536
	ds_write_b64 v22, v[72:73] offset:1792
	v_pk_mul_f32 v[74:75], v[66:67], v[78:79] op_sel_hi:[1,0]
	v_pk_mul_f32 v[64:65], v[66:67], v[78:79] op_sel:[0,1] op_sel_hi:[1,1]
	v_lshlrev_b32_e32 v70, 16, v55
	v_and_b32_e32 v71, 0xffff0000, v55
	ds_write_b64 v22, v[74:75] offset:2048
	ds_write_b64 v22, v[64:65] offset:2304
	v_pk_mul_f32 v[72:73], v[66:67], v[70:71] op_sel_hi:[1,0]
	v_pk_mul_f32 v[78:79], v[66:67], v[70:71] op_sel:[0,1] op_sel_hi:[1,1]
	s_nop 0
	ds_write_b64 v22, v[72:73] offset:2560
	ds_write_b64 v22, v[78:79] offset:2816
	s_and_saveexec_b64 s[60:61], s[42:43]
	s_cbranch_execz .Lprod_rk_skip_0_0
	global_store_dword v10, v76, s[62:63]
.Lprod_rk_skip_0_0:
	s_mov_b64 exec, -1
	v_lshlrev_b32_e32 v64, 16, v49
	v_and_b32_e32 v65, 0xffff0000, v49
	v_pk_add_f32 v[72:73], v[64:65], -1.0 op_sel_hi:[1,0]
	v_lshlrev_b32_e32 v66, 16, v48
	v_and_b32_e32 v67, 0xffff0000, v48
	v_pk_fma_f32 v[72:73], v[6:7], v[72:73], 1.0 op_sel_hi:[1,1,0]
	v_and_b32_e32 v69, 0xffff0000, v50
	v_pk_mul_f32 v[70:71], v[4:5], v[66:67]
	v_pk_mul_f32 v[66:67], v[72:73], v[66:67]
	v_lshlrev_b32_e32 v68, 16, v50
	v_mul_f32_e32 v75, v67, v69
	v_pk_mul_f32 v[72:73], v[70:71], v[70:71]
	v_mul_f32_e32 v74, v66, v68
	v_mul_f32_e32 v75, v9, v75
	v_add_f32_e32 v76, v72, v73
	v_fmac_f32_e32 v75, v8, v74
	v_cndmask_b32_e64 v74, v75, v76, s[8:9]
	v_cndmask_b32_e64 v76, v76, v75, s[8:9]
	v_cvt_f32_f16_e32 v77, v51
	v_cvt_f32_f16_sdwa v78, v51 dst_sel:DWORD dst_unused:UNUSED_PAD src0_sel:WORD_1
	v_add_f32_dpp v76, v76, v74 quad_perm:[1,0,3,2] row_mask:0xf bank_mask:0xf bound_ctrl:1
	v_mul_f32_e32 v77, 0x3fb8aa3b, v77
	s_nop 0
	v_add_f32_dpp v76, v76, v76 quad_perm:[2,3,0,1] row_mask:0xf bank_mask:0xf bound_ctrl:1
	v_exp_f32_e32 v72, v77
	v_mul_f32_e32 v77, 0x3fb8aa3b, v78
	v_add_f32_dpp v76, v76, v76 row_ror:4 row_mask:0xf bank_mask:0xf bound_ctrl:1
	v_exp_f32_e32 v73, v77
	s_nop 0
	v_add_f32_dpp v76, v76, v76 row_ror:8 row_mask:0xf bank_mask:0xf bound_ctrl:1
	v_mov_b32_e32 v74, v76
	s_nop 1
	v_permlane16_swap_b32_e32 v76, v74
	v_add_f32_e32 v76, v76, v74
	s_nop 1
	v_mov_b32_dpp v74, v76 quad_perm:[1,0,3,2] row_mask:0xf bank_mask:0xf bound_ctrl:1
	v_cndmask_b32_e64 v75, v74, v76, s[8:9]
	v_max_f32_e32 v75, v75, v75
	v_max_f32_e32 v75, 0x179abe15, v75
	v_rsq_f32_e32 v42, v75
	v_cndmask_b32_e64 v76, v76, v74, s[8:9]
	v_lshlrev_b32_e32 v74, 16, v56
	v_pk_mul_f32 v[70:71], v[70:71], v[42:43] op_sel_hi:[1,0] neg_lo:[0,1] neg_hi:[0,1]
	ds_write_b64 v22, v[72:73] offset:6656
	v_and_b32_e32 v75, 0xffff0000, v56
	v_pk_mul_f32 v[64:65], v[70:71], v[64:65] neg_lo:[1,0] neg_hi:[1,0]
	v_mov_b32_e32 v72, v71
	v_lshlrev_b32_e32 v71, 16, v40
	ds_write_b64 v22, v[64:65] offset:6912
	v_and_b32_e32 v73, 0xffff0000, v40
	v_pk_mul_f32 v[78:79], v[66:67], v[74:75] op_sel_hi:[1,0]
	ds_write_b128 v21, v[70:73] offset:6144
	v_pk_mul_f32 v[74:75], v[66:67], v[74:75] op_sel:[0,1] op_sel_hi:[1,1]
	v_lshlrev_b32_e32 v64, 16, v57
	v_and_b32_e32 v65, 0xffff0000, v57
	ds_write_b64 v22, v[78:79] offset:7168
	ds_write_b64 v22, v[74:75] offset:7424
	v_pk_mul_f32 v[70:71], v[66:67], v[64:65] op_sel_hi:[1,0]
	v_pk_mul_f32 v[72:73], v[66:67], v[64:65] op_sel:[0,1] op_sel_hi:[1,1]
	v_lshlrev_b32_e32 v78, 16, v58
	v_and_b32_e32 v79, 0xffff0000, v58
	ds_write_b64 v22, v[70:71] offset:7680
	ds_write_b64 v22, v[72:73] offset:7936
	v_pk_mul_f32 v[74:75], v[66:67], v[78:79] op_sel_hi:[1,0]
	v_pk_mul_f32 v[64:65], v[66:67], v[78:79] op_sel:[0,1] op_sel_hi:[1,1]
	v_lshlrev_b32_e32 v70, 16, v59
	v_and_b32_e32 v71, 0xffff0000, v59
	ds_write_b64 v22, v[74:75] offset:8192
	ds_write_b64 v22, v[64:65] offset:8448
	v_pk_mul_f32 v[72:73], v[66:67], v[70:71] op_sel_hi:[1,0]
	v_pk_mul_f32 v[78:79], v[66:67], v[70:71] op_sel:[0,1] op_sel_hi:[1,1]
	s_nop 0
	ds_write_b64 v22, v[72:73] offset:8704
	ds_write_b64 v22, v[78:79] offset:8960
	s_and_saveexec_b64 s[60:61], s[42:43]
	s_cbranch_execz .Lprod_rk_skip_0_1
	global_store_dword v10, v76, s[62:63] offset:128

; DI void rwkv_scan_phase(int wv, const Params& P, LAS unsigned char* lds) {
;     ...
;                         if (ck + 2 < nck) { RW_LOADG(ck + 2) } }
.Lprod_no_rl_0:
	s_cmp_gt_i32 s57, 0x1fc
	s_cbranch_scc1 .Lprod_sync_0
	s_add_i32 s67, s57, 3
	s_lshl_b32 s67, s67, 15
	s_add_u32 s60, s28, s67
	s_addc_u32 s61, s29, 0
	global_load_dword v44, v12, s[60:61]
	global_load_dword v48, v13, s[60:61]
	s_add_u32 s60, s34, s67
	s_addc_u32 s61, s35, 0
	global_load_dword v45, v12, s[60:61]
	global_load_dword v49, v13, s[60:61]
	s_add_u32 s60, s22, s67
	s_addc_u32 s61, s23, 0
	global_load_dword v46, v12, s[60:61]
	global_load_dword v50, v13, s[60:61]
	s_add_u32 s60, s36, s67
	s_addc_u32 s61, s37, 0
	global_load_dword v47, v12, s[60:61]
	global_load_dword v51, v13, s[60:61]
	s_add_u32 s60, s30, s67
	s_addc_u32 s61, s31, 0
	global_load_dwordx4 v[52:55], v16, s[60:61]
	global_load_dwordx4 v[56:59], v17, s[60:61]
	s_add_u32 s60, s22, s67
	s_addc_u32 s61, s23, 0
	s_sub_u32 s60, s60, 0x800
	s_subb_u32 s61, s61, 0
	global_load_dword v0, v12, s[60:61]
	global_load_dword v40, v13, s[60:61]

; DI void rwkv_scan_phase(int wv, const Params& P, LAS unsigned char* lds) {
;     ...
;                     if (ck + 1 < nck) { const int cn = ck + 1, buf = cn & 1;
; #pragma unroll
;                         for (int i = 0; i < 3; ++i) { const int pp = pw + 6 * i; if (pp < 16) { const int tt = 2 * pp + hf; const size_t row = (size_t)b * SEQ + cn * RW_T + tt;
.Lprod_half_1:
	s_cmp_gt_i32 s57, 0x1fe
	s_cbranch_scc1 .Lprod_sync_1
	s_add_i32 s67, s57, 1
	v_add_u32_e32 v22, 0xc000, v2
	v_add_u32_e32 v21, v80, v22
	v_mov_b32_e32 v23, 0x1e100
	v_lshl_add_u32 v23, v1, 3, v23
	s_lshl_b32 s60, s67, 10
	s_add_u32 s62, s50, s60
	s_addc_u32 s63, s51, 0
	s_cmp_gt_i32 s57, 0x1fd
	s_cbranch_scc1 .Lprod_w0_1
	s_waitcnt vmcnt(12)
	s_branch .Lprod_wd_1

; #define LAS __attribute__((address_space(3)))
; DI float bflo(unsigned u) { return __uint_as_float(u << 16); }
; DI float bfhi(unsigned u) { return __uint_as_float(u & 0xffff0000u); }
; template <int CTRL> DI float dpp_f(float v) { return __builtin_bit_cast(float, __builtin_amdgcn_update_dpp(0, __builtin_bit_cast(int, v), CTRL, 0xf, 0xf, true)); }
; DI void rwkv_scan_phase(int wv, const Params& P, LAS unsigned char* lds) {
;     ...
;                         for (int i = 0; i < 3; ++i) { const int pp = pw + 6 * i; if (pp < 16) { const int tt = 2 * pp + hf; const size_t row = (size_t)b * SEQ + cn * RW_T + tt;
;                             const f32x2 k = {bflo(gk[i]), bfhi(gk[i])}, a = {bflo(ga[i]), bfhi(ga[i])}, r = {bflo(gr[i]), bfhi(gr[i])};
;                             const h16x2 lh = __builtin_bit_cast(h16x2, gl[i]);
;                             const f32x2 kr = k * kkw2, kp = k * ((a - 1.f) * kaw2 + 1.f);
;                             const float sp = kr[0] * kr[0] + kr[1] * kr[1], rp = r[0] * kp[0] * rkw2[0] + r[1] * kp[1] * rkw2[1];
;                             const bool odd = lane & 1;
;                             float red = (odd ? rp : sp) + dpp_f<0xB1>(odd ? sp : rp);
;                             red += dpp_f<0x4E>(red); red += dpp_f<0x124>(red); red += dpp_f<0x128>(red);
;                             { auto x = __builtin_amdgcn_permlane16_swap(__float_as_uint(red), __float_as_uint(red), false, false); red = __uint_as_float(x[0]) + __uint_as_float(x[1]); }
;                             const float oth = dpp_f<0xB1>(red); const float ss = odd ? oth : red, rks = odd ? red : oth;
;                             const f32x2 kk = kr * __builtin_amdgcn_rsqf(fmaxf(ss, 1e-24f));
;                             LAS float* d = stg + ((buf * RW_T + tt) * 5) * 64 + 2 * c2;
;                             *(LAS f32x2*)(d) = -kk; *(LAS f32x2*)(d + 64) = (f32x2){__expf((float)lh[0]), __expf((float)lh[1])}; *(LAS f32x2*)(d + 128) = kk * a; *(LAS f32x2*)(d + 192) = kp; *(LAS f32x2*)(d + 256) = r;
;                             if (rg == 0 && c2 == 0) RK[row * 16 + h] = rks;
;                             if (c2 < 8) vst[(buf * RW_T + tt) * 8 + c2] = gv[i]; } }
.Lprod_wd_1:
	v_lshlrev_b32_e32 v64, 16, v25
	v_and_b32_e32 v65, 0xffff0000, v25
	v_pk_add_f32 v[72:73], v[64:65], -1.0 op_sel_hi:[1,0]
	v_lshlrev_b32_e32 v66, 16, v24
	v_and_b32_e32 v67, 0xffff0000, v24
	v_pk_fma_f32 v[72:73], v[6:7], v[72:73], 1.0 op_sel_hi:[1,1,0]
	v_and_b32_e32 v69, 0xffff0000, v26
	v_pk_mul_f32 v[70:71], v[4:5], v[66:67]
	v_pk_mul_f32 v[66:67], v[72:73], v[66:67]
	v_lshlrev_b32_e32 v68, 16, v26
	v_mul_f32_e32 v75, v67, v69
	v_pk_mul_f32 v[72:73], v[70:71], v[70:71]
	v_mul_f32_e32 v74, v66, v68
	v_mul_f32_e32 v75, v9, v75
	v_add_f32_e32 v76, v72, v73
	v_fmac_f32_e32 v75, v8, v74
	v_cndmask_b32_e64 v74, v75, v76, s[8:9]
	v_cndmask_b32_e64 v76, v76, v75, s[8:9]
	v_cvt_f32_f16_e32 v77, v27
	v_cvt_f32_f16_sdwa v78, v27 dst_sel:DWORD dst_unused:UNUSED_PAD src0_sel:WORD_1
	v_add_f32_dpp v76, v76, v74 quad_perm:[1,0,3,2] row_mask:0xf bank_mask:0xf bound_ctrl:1
	v_mul_f32_e32 v77, 0x3fb8aa3b, v77
	s_nop 0
	v_add_f32_dpp v76, v76, v76 quad_perm:[2,3,0,1] row_mask:0xf bank_mask:0xf bound_ctrl:1
	v_exp_f32_e32 v72, v77
	v_mul_f32_e32 v77, 0x3fb8aa3b, v78
	v_add_f32_dpp v76, v76, v76 row_ror:4 row_mask:0xf bank_mask:0xf bound_ctrl:1
	v_exp_f32_e32 v73, v77
	s_nop 0
	v_add_f32_dpp v76, v76, v76 row_ror:8 row_mask:0xf bank_mask:0xf bound_ctrl:1
	v_mov_b32_e32 v74, v76
	s_nop 1
	v_permlane16_swap_b32_e32 v76, v74
	v_add_f32_e32 v76, v76, v74
	s_nop 1
	v_mov_b32_dpp v74, v76 quad_perm:[1,0,3,2] row_mask:0xf bank_mask:0xf bound_ctrl:1
	v_cndmask_b32_e64 v75, v74, v76, s[8:9]
	v_max_f32_e32 v75, v75, v75
	v_max_f32_e32 v75, 0x179abe15, v75
	v_rsq_f32_e32 v42, v75
	v_cndmask_b32_e64 v76, v76, v74, s[8:9]
	v_lshlrev_b32_e32 v74, 16, v32
	v_pk_mul_f32 v[70:71], v[70:71], v[42:43] op_sel_hi:[1,0] neg_lo:[0,1] neg_hi:[0,1]
	ds_write_b64 v22, v[72:73] offset:512
	v_and_b32_e32 v75, 0xffff0000, v32
	v_pk_mul_f32 v[64:65], v[70:71], v[64:65] neg_lo:[1,0] neg_hi:[1,0]
	v_mov_b32_e32 v72, v71
	v_lshlrev_b32_e32 v71, 16, v3
	ds_write_b64 v22, v[64:65] offset:768
	v_and_b32_e32 v73, 0xffff0000, v3
	v_pk_mul_f32 v[78:79], v[66:67], v[74:75] op_sel_hi:[1,0]
	ds_write_b128 v21, v[70:73]
	v_pk_mul_f32 v[74:75], v[66:67], v[74:75] op_sel:[0,1] op_sel_hi:[1,1]
	v_lshlrev_b32_e32 v64, 16, v33
	v_and_b32_e32 v65, 0xffff0000, v33
	ds_write_b64 v22, v[78:79] offset:1024
	ds_write_b64 v22, v[74:75] offset:1280
	v_pk_mul_f32 v[70:71], v[66:67], v[64:65] op_sel_hi:[1,0]
	v_pk_mul_f32 v[72:73], v[66:67], v[64:65] op_sel:[0,1] op_sel_hi:[1,1]
	v_lshlrev_b32_e32 v78, 16, v34
	v_and_b32_e32 v79, 0xffff0000, v34
	ds_write_b64 v22, v[70:71] offset:1536
	ds_write_b64 v22, v[72:73] offset:1792
	v_pk_mul_f32 v[74:75], v[66:67], v[78:79] op_sel_hi:[1,0]
	v_pk_mul_f32 v[64:65], v[66:67], v[78:79] op_sel:[0,1] op_sel_hi:[1,1]
	v_lshlrev_b32_e32 v70, 16, v35
	v_and_b32_e32 v71, 0xffff0000, v35
	ds_write_b64 v22, v[74:75] offset:2048
	ds_write_b64 v22, v[64:65] offset:2304
	v_pk_mul_f32 v[72:73], v[66:67], v[70:71] op_sel_hi:[1,0]
	v_pk_mul_f32 v[78:79], v[66:67], v[70:71] op_sel:[0,1] op_sel_hi:[1,1]
	s_nop 0
	ds_write_b64 v22, v[72:73] offset:2560
	ds_write_b64 v22, v[78:79] offset:2816
	s_and_saveexec_b64 s[60:61], s[42:43]
	s_cbranch_execz .Lprod_rk_skip_1_0
	global_store_dword v10, v76, s[62:63]
.Lprod_rk_skip_1_0:
	s_mov_b64 exec, -1
	v_lshlrev_b32_e32 v64, 16, v29
	v_and_b32_e32 v65, 0xffff0000, v29
	v_pk_add_f32 v[72:73], v[64:65], -1.0 op_sel_hi:[1,0]
	v_lshlrev_b32_e32 v66, 16, v28
	v_and_b32_e32 v67, 0xffff0000, v28
	v_pk_fma_f32 v[72:73], v[6:7], v[72:73], 1.0 op_sel_hi:[1,1,0]
	v_and_b32_e32 v69, 0xffff0000, v30
	v_pk_mul_f32 v[70:71], v[4:5], v[66:67]
	v_pk_mul_f32 v[66:67], v[72:73], v[66:67]
	v_lshlrev_b32_e32 v68, 16, v30
	v_mul_f32_e32 v75, v67, v69
	v_pk_mul_f32 v[72:73], v[70:71], v[70:71]
	v_mul_f32_e32 v74, v66, v68
	v_mul_f32_e32 v75, v9, v75
	v_add_f32_e32 v76, v72, v73
	v_fmac_f32_e32 v75, v8, v74
	v_cndmask_b32_e64 v74, v75, v76, s[8:9]
	v_cndmask_b32_e64 v76, v76, v75, s[8:9]
	v_cvt_f32_f16_e32 v77, v31
	v_cvt_f32_f16_sdwa v78, v31 dst_sel:DWORD dst_unused:UNUSED_PAD src0_sel:WORD_1
	v_add_f32_dpp v76, v76, v74 quad_perm:[1,0,3,2] row_mask:0xf bank_mask:0xf bound_ctrl:1
	v_mul_f32_e32 v77, 0x3fb8aa3b, v77
	s_nop 0
	v_add_f32_dpp v76, v76, v76 quad_perm:[2,3,0,1] row_mask:0xf bank_mask:0xf bound_ctrl:1
	v_exp_f32_e32 v72, v77
	v_mul_f32_e32 v77, 0x3fb8aa3b, v78
	v_add_f32_dpp v76, v76, v76 row_ror:4 row_mask:0xf bank_mask:0xf bound_ctrl:1
	v_exp_f32_e32 v73, v77
	s_nop 0
	v_add_f32_dpp v76, v76, v76 row_ror:8 row_mask:0xf bank_mask:0xf bound_ctrl:1
	v_mov_b32_e32 v74, v76
	s_nop 1
	v_permlane16_swap_b32_e32 v76, v74
	v_add_f32_e32 v76, v76, v74
	s_nop 1
	v_mov_b32_dpp v74, v76 quad_perm:[1,0,3,2] row_mask:0xf bank_mask:0xf bound_ctrl:1
	v_cndmask_b32_e64 v75, v74, v76, s[8:9]
	v_max_f32_e32 v75, v75, v75
	v_max_f32_e32 v75, 0x179abe15, v75
	v_rsq_f32_e32 v42, v75
	v_cndmask_b32_e64 v76, v76, v74, s[8:9]
	v_lshlrev_b32_e32 v74, 16, v36
	v_pk_mul_f32 v[70:71], v[70:71], v[42:43] op_sel_hi:[1,0] neg_lo:[0,1] neg_hi:[0,1]
	ds_write_b64 v22, v[72:73] offset:6656
	v_and_b32_e32 v75, 0xffff0000, v36
	v_pk_mul_f32 v[64:65], v[70:71], v[64:65] neg_lo:[1,0] neg_hi:[1,0]
	v_mov_b32_e32 v72, v71
	v_lshlrev_b32_e32 v71, 16, v43
	ds_write_b64 v22, v[64:65] offset:6912
	v_and_b32_e32 v73, 0xffff0000, v43
	v_pk_mul_f32 v[78:79], v[66:67], v[74:75] op_sel_hi:[1,0]
	ds_write_b128 v21, v[70:73] offset:6144
	v_pk_mul_f32 v[74:75], v[66:67], v[74:75] op_sel:[0,1] op_sel_hi:[1,1]
	v_lshlrev_b32_e32 v64, 16, v37
	v_and_b32_e32 v65, 0xffff0000, v37
	ds_write_b64 v22, v[78:79] offset:7168
	ds_write_b64 v22, v[74:75] offset:7424
	v_pk_mul_f32 v[70:71], v[66:67], v[64:65] op_sel_hi:[1,0]
	v_pk_mul_f32 v[72:73], v[66:67], v[64:65] op_sel:[0,1] op_sel_hi:[1,1]
	v_lshlrev_b32_e32 v78, 16, v38
	v_and_b32_e32 v79, 0xffff0000, v38
	ds_write_b64 v22, v[70:71] offset:7680
	ds_write_b64 v22, v[72:73] offset:7936
	v_pk_mul_f32 v[74:75], v[66:67], v[78:79] op_sel_hi:[1,0]
	v_pk_mul_f32 v[64:65], v[66:67], v[78:79] op_sel:[0,1] op_sel_hi:[1,1]
	v_lshlrev_b32_e32 v70, 16, v39
	v_and_b32_e32 v71, 0xffff0000, v39
	ds_write_b64 v22, v[74:75] offset:8192
	ds_write_b64 v22, v[64:65] offset:8448
	v_pk_mul_f32 v[72:73], v[66:67], v[70:71] op_sel_hi:[1,0]
	v_pk_mul_f32 v[78:79], v[66:67], v[70:71] op_sel:[0,1] op_sel_hi:[1,1]
	s_nop 0
	ds_write_b64 v22, v[72:73] offset:8704
	ds_write_b64 v22, v[78:79] offset:8960
	s_and_saveexec_b64 s[60:61], s[42:43]
	s_cbranch_execz .Lprod_rk_skip_1_1
	global_store_dword v10, v76, s[62:63] offset:128

; DI void rwkv_scan_phase(int wv, const Params& P, LAS unsigned char* lds) {
;     ...
;                         if (ck + 2 < nck) { RW_LOADG(ck + 2) } }
.Lprod_no_rl_1:
	s_cmp_gt_i32 s57, 0x1fc
	s_cbranch_scc1 .Lprod_sync_1
	s_add_i32 s67, s57, 3
	s_lshl_b32 s67, s67, 15
	s_add_u32 s60, s28, s67
	s_addc_u32 s61, s29, 0
	global_load_dword v24, v12, s[60:61]
	global_load_dword v28, v13, s[60:61]
	s_add_u32 s60, s34, s67
	s_addc_u32 s61, s35, 0
	global_load_dword v25, v12, s[60:61]
	global_load_dword v29, v13, s[60:61]
	s_add_u32 s60, s22, s67
	s_addc_u32 s61, s23, 0
	global_load_dword v26, v12, s[60:61]
	global_load_dword v30, v13, s[60:61]
	s_add_u32 s60, s36, s67
	s_addc_u32 s61, s37, 0
	global_load_dword v27, v12, s[60:61]
	global_load_dword v31, v13, s[60:61]
	s_add_u32 s60, s30, s67
	s_addc_u32 s61, s31, 0
	global_load_dwordx4 v[32:35], v16, s[60:61]
	global_load_dwordx4 v[36:39], v17, s[60:61]
	s_add_u32 s60, s22, s67
	s_addc_u32 s61, s23, 0
	s_sub_u32 s60, s60, 0x800
	s_subb_u32 s61, s61, 0
	global_load_dword v3, v12, s[60:61]
	global_load_dword v43, v13, s[60:61]

; #define LAS __attribute__((address_space(3)))
; DI unsigned pk2(float lo, float hi) { f32x2 v = {lo, hi}; bf16x2_t b = __builtin_convertvector(v, bf16x2_t); return __builtin_bit_cast(unsigned, b); }
; DI float row16_sum(float v) { v += dpp_f<0xB1>(v); v += dpp_f<0x4E>(v); v += dpp_f<0x141>(v); v += dpp_f<0x140>(v); return v; }
; DI void rwkv_scan_phase(int wv, const Params& P, LAS unsigned char* lds) {
;     ...
;                 {
;                     if (ck >= 1) { const LAS float* yb = ybuf + ((ck - 1) & 1) * RW_T * 128;
; #pragma unroll 2
;                         for (int it = pw; it < 64; it += 6) { const float y = row16_sum(yb[it * 64 + lane]);
;                             const float y0 = __builtin_bit_cast(float, __builtin_amdgcn_readlane(__builtin_bit_cast(int, y), 0)), y1 = __builtin_bit_cast(float, __builtin_amdgcn_readlane(__builtin_bit_cast(int, y), 16)),
;                                         y2 = __builtin_bit_cast(float, __builtin_amdgcn_readlane(__builtin_bit_cast(int, y), 32)), y3 = __builtin_bit_cast(float, __builtin_amdgcn_readlane(__builtin_bit_cast(int, y), 48));
;                             if (lane == 0) { u32x2 w; w.x = pk2(y0, y1); w.y = pk2(y2, y3); *(u32x2*)(YS + ((size_t)b * SEQ + (ck - 1) * RW_T + (it >> 1)) * 1024 + h * 64 + rg * 8 + (it & 1) * 4) = w; } } }
.Lprod_flusher:
	s_and_b32 s55, s55, 1
	s_and_b32 s67, s46, 7
	s_bfe_u32 s59, s46, 0x40003
	s_lshl_b32 s61, s59, 6
	v_mbcnt_lo_u32_b32 v0, -1, 0
	v_mbcnt_hi_u32_b32 v0, -1, v0
	v_and_b32_e32 v36, 7, v0
	v_lshrrev_b32_e32 v37, 3, v0
	s_lshl_b32 s66, s55, 3
	v_add_u32_e32 v37, s66, v37
	v_lshlrev_b32_e32 v11, 9, v37
	v_lshl_add_u32 v11, v36, 6, v11
	v_add_u32_e32 v11, 0x18000, v11
	s_lshr_b32 s66, s46, 7
	s_lshl_b32 s66, s66, 13
	v_add_u32_e32 v37, s66, v37
	v_lshlrev_b32_e32 v37, 11, v37
	s_lshl_b32 s66, s67, 3
	s_add_i32 s66, s66, s61
	v_add_u32_e32 v38, s66, v36
	v_lshl_add_u32 v20, v38, 1, v37
	s_mov_b32 s57, -1
	s_mov_b32 s69, 0
.Lflush_loop:
	s_cmp_lt_i32 s57, 2
	s_cbranch_scc1 .Lflush_sync
	s_add_i32 s67, s57, -2
	v_add_u32_e32 v21, s69, v11
	s_add_i32 s69, s69, 0x2000
	s_cmp_eq_u32 s69, 0x6000
	s_cselect_b32 s69, 0, s69
	ds_read_b128 v[24:27], v21
	ds_read_b128 v[28:31], v21 offset:16
	ds_read_b128 v[32:35], v21 offset:32
	ds_read_b128 v[36:39], v21 offset:48
	s_lshl_b32 s67, s67, 15
	s_add_u32 s60, s44, s67
	s_addc_u32 s61, s45, 0
	s_waitcnt lgkmcnt(0)
	v_pk_add_f32 v[24:25], v[24:25], v[26:27]
	v_pk_add_f32 v[28:29], v[28:29], v[30:31]
	v_pk_add_f32 v[32:33], v[32:33], v[34:35]
	v_pk_add_f32 v[36:37], v[36:37], v[38:39]
	v_pk_add_f32 v[24:25], v[24:25], v[28:29]
	v_pk_add_f32 v[32:33], v[32:33], v[36:37]
	s_nop 0
	v_pk_add_f32 v[24:25], v[24:25], v[32:33]
	s_nop 0
	v_add_f32_e32 v24, v24, v25
	s_nop 1
	v_mov_b32_dpp v25, v24 quad_perm:[1,0,3,2] row_mask:0xf bank_mask:0xf bound_ctrl:1
	s_nop 0
	v_cvt_pk_bf16_f32 v24, v24, v25
	s_mov_b64 exec, s[8:9]
	global_store_dword v20, v24, s[60:61]
	s_mov_b64 exec, -1
